# pass1: lower-bound and forget-logit loads hoisted above the unit's first barrier (as in pass3)
# speedup vs baseline: 1.0036x; 1.0036x over previous
.LBB0_535:
	s_and_b64 vcc, exec, s[0:1]
	s_cbranch_vccz .LBB0_510
	v_mov_b32_e32 v2, v208
	s_load_dwordx2 s[98:99], s[66:67], 0x18
	s_lshl_b32 s0, s36, 1
	v_ashrrev_i32_e32 v0, 2, v2
	s_and_b32 s2, s0, 0x180
	v_and_b32_e32 v13, 0xffffffe0, v0
	v_and_b32_e32 v68, 31, v2
	v_add_u32_e32 v0, s2, v13
	v_or_b32_e32 v4, v0, v68
	v_ashrrev_i32_e32 v5, 31, v4
	s_lshl_b32 s0, s36, 4
	v_lshlrev_b64 v[4:5], 15, v[4:5]
	s_and_b32 s0, s0, 0xfffff000
	v_lshl_add_u64 v[4:5], s[96:97], 0, v[4:5]
	s_ashr_i32 s1, s0, 31
	v_lshl_add_u64 v[4:5], s[0:1], 1, v[4:5]
	s_lshl_b32 s1, s36, 6
	s_and_b32 s1, s1, 0xfc0
	v_bfe_u32 v12, v2, 5, 1
	s_lshl_b32 s54, s1, 1
	v_lshl_add_u64 v[4:5], v[4:5], 0, s[54:55]
	v_lshlrev_b32_e32 v0, 4, v12
	v_lshl_add_u64 v[4:5], v[4:5], 0, v[0:1]
	global_load_dwordx4 v[30:33], v[4:5], off
	global_load_dwordx4 v[26:29], v[4:5], off offset:32
	global_load_dwordx4 v[22:25], v[4:5], off offset:64
	global_load_dwordx4 v[18:21], v[4:5], off offset:96
	v_and_b32_e32 v3, 0x7f, v2
	s_waitcnt lgkmcnt(0)
	v_or_b32_e32 v70, s2, v3
	v_lshlrev_b32_e32 v70, 2, v70
	global_load_dword v90, v70, s[98:99]
	global_load_dword v91, v70, s[98:99] offset:2048
	v_ashrrev_i32_e32 v69, 7, v2
	s_or_b32 vcc_lo, s1, s0
	v_lshl_add_u32 v71, v69, 4, vcc_lo
	v_mov_b64_e32 v[72:73], s[78:79]
	s_movk_i32 vcc_lo, 0x1c00
	v_mad_i64_i32 v[72:73], vcc, v71, vcc_lo, v[72:73]
	v_lshlrev_b32_e32 v74, 1, v3
	v_mov_b32_e32 v75, 0
	v_lshl_add_u64 v[72:73], v[72:73], 0, v[74:75]
	s_nop 1
	s_lshl_b32 vcc_lo, s2, 1
	s_mov_b32 vcc_hi, 0
	v_lshl_add_u64 v[72:73], v[72:73], 0, vcc
	s_mov_b64 vcc, 0x10d01200
	v_lshl_add_u64 v[72:73], v[72:73], 0, vcc
	s_mov_b64 vcc, 0x3800
	global_load_ushort v100, v[72:73], off offset:-3584
	global_load_ushort v101, v[72:73], off offset:3584
	v_lshl_add_u64 v[76:77], v[72:73], 0, vcc
	global_load_ushort v102, v[76:77], off offset:-3584
	global_load_ushort v103, v[76:77], off offset:3584
	v_lshl_add_u64 v[72:73], v[76:77], 0, vcc
	global_load_ushort v104, v[72:73], off offset:-3584
	global_load_ushort v105, v[72:73], off offset:3584
	v_lshl_add_u64 v[76:77], v[72:73], 0, vcc
	global_load_ushort v106, v[76:77], off offset:-3584
	global_load_ushort v107, v[76:77], off offset:3584
	v_lshl_add_u64 v[72:73], v[76:77], 0, vcc
	global_load_ushort v108, v[72:73], off offset:-3584
	global_load_ushort v109, v[72:73], off offset:3584
	v_lshl_add_u64 v[76:77], v[72:73], 0, vcc
	global_load_ushort v110, v[76:77], off offset:-3584
	global_load_ushort v111, v[76:77], off offset:3584
	v_lshl_add_u64 v[72:73], v[76:77], 0, vcc
	global_load_ushort v112, v[72:73], off offset:-3584
	global_load_ushort v113, v[72:73], off offset:3584
	v_lshl_add_u64 v[76:77], v[72:73], 0, vcc
	global_load_ushort v114, v[76:77], off offset:-3584
	global_load_ushort v115, v[76:77], off offset:3584
	s_andn2_b64 vcc, exec, s[38:39]
	v_mov_b32_e32 v5, 0
	s_barrier
	s_cbranch_vccnz .LBB0_538
	s_waitcnt vmcnt(0) lgkmcnt(0)
	v_sub_f32_e32 v0, v90, v91
	v_mul_f32_e32 v0, 0x3fb8aa3b, v0
	v_exp_f32_e32 v0, v0
	s_nop 0
	v_add_f32_e32 v0, 1.0, v0
	v_div_scale_f32 v4, s[4:5], v0, v0, 1.0
	v_rcp_f32_e32 v5, v4
	v_div_scale_f32 v6, vcc, 1.0, v0, 1.0
	v_fma_f32 v7, -v4, v5, 1.0
	v_fmac_f32_e32 v5, v7, v5
	v_mul_f32_e32 v7, v6, v5
	v_fma_f32 v8, -v4, v7, v6
	v_fmac_f32_e32 v7, v8, v5
	v_fma_f32 v4, -v4, v7, v6
	v_div_fmas_f32 v4, v4, v5, v7
	v_div_fixup_f32 v5, v4, v0, 1.0
.LBB0_538:
	v_ashrrev_i32_e32 v4, 7, v2
	s_lshl_b32 s54, s2, 1
	v_sub_f32_e32 v0, 1.0, v5
	s_mov_b64 s[0:1], -1
	s_waitcnt vmcnt(0)
	v_mov_b32_e32 v7, v100
	v_mov_b32_e32 v11, v101
	v_mov_b32_e32 v15, v102
	v_mov_b32_e32 v16, v103
	v_mov_b32_e32 v34, v104
	v_mov_b32_e32 v38, v105
	v_mov_b32_e32 v41, v106
	v_mov_b32_e32 v44, v107
	v_mov_b32_e32 v45, v108
	v_mov_b32_e32 v42, v109
	v_mov_b32_e32 v39, v110
	v_mov_b32_e32 v36, v111
	v_mov_b32_e32 v17, v112
	v_mov_b32_e32 v9, v113
	v_mov_b32_e32 v8, v114
	v_mov_b32_e32 v6, v115
	v_lshlrev_b32_e32 v14, 16, v7
	v_mul_f32_e64 v7, |v14|, s47
	v_exp_f32_e32 v7, v7
	v_cmp_le_f32_e32 vcc, 0, v14
	v_add_f32_e32 v35, 1.0, v7
	v_rcp_f32_e32 v10, v35
	s_nop 0
	v_mul_f32_e32 v7, v7, v10
	v_cndmask_b32_e32 v10, v7, v10, vcc
	s_and_b64 vcc, exec, s[48:49]
	s_cbranch_vccz .LBB0_540
	v_fma_f32 v7, v0, v10, v5
	v_cmp_gt_f32_e32 vcc, s35, v7
	s_mov_b32 s0, 0x7f800000
	s_nop 0
	v_cndmask_b32_e64 v37, 0, 32, vcc
	v_ldexp_f32 v7, v7, v37
	v_log_f32_e32 v7, v7
	v_cndmask_b32_e32 v37, 0, v212, vcc
	v_mul_f32_e32 v40, 0x3f317217, v7
	v_fma_f32 v40, v7, s24, -v40
	v_fmac_f32_e32 v40, 0x3377d1cf, v7
	v_fmac_f32_e32 v40, 0x3f317217, v7
	v_cmp_lt_f32_e64 vcc, |v7|, s0
	s_mov_b64 s[0:1], 0
	s_nop 0
	v_cndmask_b32_e32 v7, v7, v40, vcc
	v_sub_f32_e32 v7, v7, v37
